# v18 + sg_item mixing/epilogue rewritten: unrolled wave-uniform tile loop, B fragments read once, batched A reads, bias loads up front, cheap store addressing
# speedup vs baseline: 1.0042x; 1.0042x over previous
; __device__ __forceinline__ void unpack8(const u32x4& w, f32x4& v0, f32x4& v1) { v0[0] = bflo(w.x); v0[1] = bfhi(w.x); v0[2] = bflo(w.y); v0[3] = bfhi(w.y); v1[0] = bflo(w.z); v1[1] = bfhi(w.z); v1[2] = bflo(w.w); v1[3] = bfhi(w.w); }
; __device__ __forceinline__ void sg_item(const Bufs& B, int l, int s, int it, unsigned char* shm) {
;     ...
;     const int t = tid >> 2, part = tid & 3, cl0 = part * 32, cg0 = g * 128 + cl0;
;     u32x4 sv[16], vq[4], uv[4]; f32x4 wv[8];
;     {
;         const u32x4* vp = (const u32x4*)(B.bufC + (size_t)(m0 + t) * 1024 + 512 + part * 128);
; #pragma unroll
;         for (int i = 0; i < 16; ++i) sv[i] = vp[i];
;         const u32x4* vqp = (const u32x4*)(B.bufC + (size_t)(m0 + t) * 1024 + 512 + cg0);
; #pragma unroll
;         for (int i = 0; i < 4; ++i) vq[i] = vqp[i];
;         const float* sw = IN(19) + (size_t)(l * 4 + g) * 16384;
; #pragma unroll
;         for (int i = 0; i < 8; ++i) wv[i] = *(const f32x4*)(sw + (tid + 512 * i) * 4);
;     }
;     __syncthreads();
;     {
;         float sum = 0.f, sq = 0.f;
; #pragma unroll
;         for (int i = 0; i < 16; ++i) { f32x4 a, bb; unpack8(sv[i], a, bb);
;             sum += (a[0] + a[1]) + (a[2] + a[3]) + (bb[0] + bb[1]) + (bb[2] + bb[3]);
;             sq += a[0] * a[0] + a[1] * a[1] + a[2] * a[2] + a[3] * a[3] + bb[0] * bb[0] + bb[1] * bb[1] + bb[2] * bb[2] + bb[3] * bb[3]; }
.LBB0_547:
	v_mov_b32_e32 v114, v179
	s_lshl_b32 s2, s27, 5
	s_and_b32 s38, s2, 0xffffff80
	v_ashrrev_i32_e32 v116, 2, v114
	v_add_u32_e32 v0, s38, v116
	v_ashrrev_i32_e32 v1, 31, v0
	v_and_b32_e32 v115, 3, v114
	v_lshlrev_b64 v[0:1], 11, v[0:1]
	v_lshl_add_u64 v[0:1], s[16:17], 0, v[0:1]
	v_lshlrev_b32_e32 v176, 8, v115
	v_lshl_add_u64 v[2:3], v[0:1], 0, v[176:177]
	global_load_dwordx4 v[96:99], v[2:3], off offset:1072
	global_load_dwordx4 v[100:103], v[2:3], off offset:1056
	global_load_dwordx4 v[104:107], v[2:3], off offset:1040
	global_load_dwordx4 v[108:111], v[2:3], off offset:1024
	global_load_dwordx4 v[80:83], v[2:3], off offset:1136
	global_load_dwordx4 v[84:87], v[2:3], off offset:1120
	global_load_dwordx4 v[88:91], v[2:3], off offset:1104
	global_load_dwordx4 v[92:95], v[2:3], off offset:1088
	global_load_dwordx4 v[64:67], v[2:3], off offset:1200
	global_load_dwordx4 v[68:71], v[2:3], off offset:1184
	global_load_dwordx4 v[72:75], v[2:3], off offset:1168
	global_load_dwordx4 v[76:79], v[2:3], off offset:1152
	global_load_dwordx4 v[48:51], v[2:3], off offset:1264
	global_load_dwordx4 v[52:55], v[2:3], off offset:1248
	global_load_dwordx4 v[56:59], v[2:3], off offset:1232
	global_load_dwordx4 v[60:63], v[2:3], off offset:1216
	s_and_b32 s20, s27, 3
	s_lshl_b32 s36, s20, 7
	v_lshl_or_b32 v117, v115, 5, s36
	v_lshlrev_b32_e32 v176, 1, v117
	s_waitcnt vmcnt(31)
	v_lshl_add_u64 v[4:5], v[0:1], 0, v[176:177]
	s_or_b32 s30, s20, s29
	global_load_dwordx4 v[0:3], v[4:5], off offset:1072
	global_load_dwordx4 v[36:39], v[4:5], off offset:1056
	global_load_dwordx4 v[40:43], v[4:5], off offset:1040
	global_load_dwordx4 v[44:47], v[4:5], off offset:1024
	s_load_dwordx2 s[2:3], s[0:1], 0x98
	s_waitcnt lgkmcnt(0)
	s_lshl_b32 s21, s30, 16
	s_add_u32 s2, s2, s21
	v_lshlrev_b32_e32 v112, 2, v114
	s_addc_u32 s3, s3, 0
	v_ashrrev_i32_e32 v113, 31, v112
	v_lshl_add_u64 v[4:5], v[112:113], 2, s[2:3]
	v_cmp_lt_i32_e32 vcc, v206, v205
	s_waitcnt vmcnt(33)
	v_add_u32_e32 v12, 0x1000, v112
	v_ashrrev_i32_e32 v13, 31, v12
	v_lshl_add_u64 v[12:13], v[12:13], 2, s[2:3]
	global_load_dwordx4 v[8:11], v[4:5], off
	s_waitcnt vmcnt(33)
	v_add_u32_e32 v16, 0x1800, v112
	global_load_dwordx4 v[12:15], v[12:13], off
	v_add_u32_e32 v4, 0x800, v112
	s_waitcnt vmcnt(33)
	v_add_u32_e32 v20, 0x2000, v112
	s_waitcnt vmcnt(32)
	v_add_u32_e32 v24, 0x2800, v112
	s_waitcnt vmcnt(31)
	v_add_u32_e32 v28, 0x3000, v112
	s_waitcnt vmcnt(30)
	v_add_u32_e32 v32, 0x3800, v112
	v_ashrrev_i32_e32 v5, 31, v4
	v_ashrrev_i32_e32 v17, 31, v16
	v_ashrrev_i32_e32 v21, 31, v20
	v_ashrrev_i32_e32 v25, 31, v24
	v_ashrrev_i32_e32 v29, 31, v28
	v_ashrrev_i32_e32 v33, 31, v32
	v_lshl_add_u64 v[4:5], v[4:5], 2, s[2:3]
	v_lshl_add_u64 v[16:17], v[16:17], 2, s[2:3]
	v_lshl_add_u64 v[20:21], v[20:21], 2, s[2:3]
	v_lshl_add_u64 v[24:25], v[24:25], 2, s[2:3]
	v_lshl_add_u64 v[28:29], v[28:29], 2, s[2:3]
	v_lshl_add_u64 v[32:33], v[32:33], 2, s[2:3]
	s_mov_b32 s2, 0x3b000000
	global_load_dwordx4 v[4:7], v[4:5], off
	s_waitcnt vmcnt(22)
	v_and_b32_e32 v134, 0xffff0000, v97
	s_waitcnt vmcnt(21)
	v_lshlrev_b32_e32 v131, 16, v100
	s_waitcnt vmcnt(20)
	v_lshlrev_b32_e32 v127, 16, v104
	s_waitcnt vmcnt(19)
	v_lshlrev_b32_e32 v123, 16, v109
	v_lshlrev_b32_e32 v122, 16, v108
	v_and_b32_e32 v118, 0xffff0000, v108
	v_and_b32_e32 v119, 0xffff0000, v109
	v_pk_mul_f32 v[108:109], v[122:123], v[122:123]
	v_lshlrev_b32_e32 v113, 16, v110
	v_fma_f32 v108, v118, v118, v108
	v_add_f32_e32 v125, v122, v118
	v_add_f32_e32 v118, v109, v108
	v_mul_f32_e32 v122, v119, v119
	v_and_b32_e32 v110, 0xffff0000, v110
	v_lshlrev_b32_e32 v120, 16, v111
	v_and_b32_e32 v121, 0xffff0000, v111
	v_and_b32_e32 v111, 0xffff0000, v104
	v_pk_add_f32 v[118:119], v[122:123], v[118:119]
	v_mul_f32_e32 v124, v113, v113
	v_pk_add_f32 v[118:119], v[124:125], v[118:119]
	v_pk_add_f32 v[124:125], v[110:111], v[112:113] op_sel_hi:[0,1]
	v_mul_f32_e32 v122, v110, v110
	v_mov_b32_e32 v123, v125
	v_pk_add_f32 v[124:125], v[120:121], v[120:121] op_sel_hi:[0,1]
	v_pk_add_f32 v[118:119], v[122:123], v[118:119]
	v_mul_f32_e32 v122, v120, v120
	v_mov_b32_e32 v123, v125
	v_lshlrev_b32_e32 v129, 16, v105
	v_pk_add_f32 v[118:119], v[122:123], v[118:119]
	v_mov_b32_e32 v122, v127
	v_mov_b32_e32 v123, v111
	v_mul_f32_e32 v124, v111, v111
	v_pk_fma_f32 v[122:123], v[122:123], v[122:123], v[124:125] op_sel_hi:[1,1,0]
	v_mul_f32_e32 v124, v129, v129
	v_and_b32_e32 v126, 0xffff0000, v106
	v_and_b32_e32 v128, 0xffff0000, v105
	v_pk_mul_f32 v[120:121], v[120:121], v[120:121]
	v_pk_add_f32 v[122:123], v[124:125], v[122:123] op_sel_hi:[0,1]
	v_mov_b32_e32 v176, v121
	v_mov_b32_e32 v110, v126
	v_lshlrev_b32_e32 v121, 16, v106
	v_pk_fma_f32 v[122:123], v[128:129], v[128:129], v[122:123]
	s_waitcnt vmcnt(17)
; __device__ __forceinline__ void unpack8(const u32x4& w, f32x4& v0, f32x4& v1) { v0[0] = bflo(w.x); v0[1] = bfhi(w.x); v0[2] = bflo(w.y); v0[3] = bfhi(w.y); v1[0] = bflo(w.z); v1[1] = bfhi(w.z); v1[2] = bflo(w.w); v1[3] = bfhi(w.w); }
; __device__ __forceinline__ void sg_item(const Bufs& B, int l, int s, int it, unsigned char* shm) {
;     ...
;         float sum = 0.f, sq = 0.f;
; #pragma unroll
;         for (int i = 0; i < 16; ++i) { f32x4 a, bb; unpack8(sv[i], a, bb);
;             sum += (a[0] + a[1]) + (a[2] + a[3]) + (bb[0] + bb[1]) + (bb[2] + bb[3]);
;             sq += a[0] * a[0] + a[1] * a[1] + a[2] * a[2] + a[3] * a[3] + bb[0] * bb[0] + bb[1] * bb[1] + bb[2] * bb[2] + bb[3] * bb[3]; }
	v_and_b32_e32 v104, 0xffff0000, v85
	v_lshlrev_b32_e32 v105, 16, v85
	v_lshlrev_b32_e32 v85, 16, v107
	v_mul_f32_e32 v124, v121, v121
	v_mov_b32_e32 v125, v129
	v_mov_b32_e32 v123, v128
	v_pk_add_f32 v[110:111], v[126:127], v[110:111]
	v_pk_add_f32 v[118:119], v[118:119], v[176:177]
	v_and_b32_e32 v176, 0xffff0000, v107
	v_mov_b32_e32 v120, v85
	v_pk_mov_b32 v[106:107], v[84:85], v[126:127] op_sel:[1,0]
	v_pk_add_f32 v[122:123], v[124:125], v[122:123]
	v_mul_f32_e32 v124, v126, v126
	v_mov_b32_e32 v125, v111
	v_pk_add_f32 v[110:111], v[124:125], v[122:123]
	v_pk_mul_f32 v[122:123], v[120:121], v[106:107]
	v_pk_add_f32 v[106:107], v[120:121], v[106:107]
	v_pk_add_f32 v[120:121], v[176:177], v[84:85] op_sel_hi:[0,1]
	v_mov_b32_e32 v123, v107
	v_pk_add_f32 v[106:107], v[122:123], v[110:111]
	v_pk_mul_f32 v[110:111], v[176:177], v[176:177]
	v_and_b32_e32 v132, 0xffff0000, v101
	v_mov_b32_e32 v111, v121
	v_lshlrev_b32_e32 v133, 16, v101
	v_pk_add_f32 v[106:107], v[110:111], v[106:107]
	v_and_b32_e32 v101, 0xffff0000, v100
	v_pk_add_f32 v[106:107], v[118:119], v[106:107]
	v_mov_b32_e32 v118, v131
	v_mov_b32_e32 v119, v101
	v_mul_f32_e32 v120, v101, v101
	v_pk_fma_f32 v[118:119], v[118:119], v[118:119], v[120:121] op_sel_hi:[1,1,0]
	v_mul_f32_e32 v120, v133, v133
	v_pk_add_f32 v[118:119], v[120:121], v[118:119] op_sel_hi:[0,1]
	v_and_b32_e32 v100, 0xffff0000, v102
	v_lshlrev_b32_e32 v111, 16, v102
	v_pk_fma_f32 v[118:119], v[132:133], v[132:133], v[118:119]
	v_mov_b32_e32 v130, v100
	v_lshlrev_b32_e32 v85, 16, v103
	v_mul_f32_e32 v120, v111, v111
	v_mov_b32_e32 v121, v133
	v_mov_b32_e32 v119, v132
	v_and_b32_e32 v176, 0xffff0000, v103
	v_pk_mov_b32 v[102:103], v[84:85], v[100:101] op_sel:[1,0]
	v_pk_add_f32 v[118:119], v[120:121], v[118:119]
	v_pk_mul_f32 v[120:121], v[100:101], v[100:101]
	v_pk_add_f32 v[100:101], v[130:131], v[100:101]
	v_mov_b32_e32 v110, v85
	v_mov_b32_e32 v121, v101
	v_pk_add_f32 v[100:101], v[120:121], v[118:119]
	v_pk_mul_f32 v[118:119], v[110:111], v[102:103]
	v_pk_add_f32 v[102:103], v[110:111], v[102:103]
	v_lshlrev_b32_e32 v135, 16, v97
	v_mov_b32_e32 v119, v103
	v_pk_mul_f32 v[102:103], v[176:177], v[176:177]
	v_pk_add_f32 v[110:111], v[176:177], v[84:85] op_sel_hi:[0,1]
	v_lshlrev_b32_e32 v85, 16, v96
	v_and_b32_e32 v97, 0xffff0000, v96
	v_pk_add_f32 v[100:101], v[118:119], v[100:101]
	v_mov_b32_e32 v103, v111
	v_mov_b32_e32 v110, v85
	v_mov_b32_e32 v111, v97
	v_mul_f32_e32 v118, v97, v97
	v_pk_fma_f32 v[110:111], v[110:111], v[110:111], v[118:119] op_sel_hi:[1,1,0]
	v_mul_f32_e32 v118, v135, v135
	v_pk_add_f32 v[100:101], v[102:103], v[100:101]
	v_and_b32_e32 v102, 0xffff0000, v98
	v_pk_add_f32 v[110:111], v[118:119], v[110:111] op_sel_hi:[0,1]
	s_waitcnt vmcnt(16)
	v_and_b32_e32 v108, 0xffff0000, v89
	v_lshlrev_b32_e32 v109, 16, v89
	v_pk_add_f32 v[100:101], v[106:107], v[100:101]
	v_and_b32_e32 v103, 16, v96
	v_mov_b32_e32 v96, v102
	v_lshlrev_b32_e32 v107, 16, v98
	v_lshlrev_b32_e32 v89, 16, v99
	v_pk_fma_f32 v[110:111], v[134:135], v[134:135], v[110:111]
	v_and_b32_e32 v176, 0xffff0000, v99
	v_pk_mov_b32 v[98:99], v[88:89], v[102:103] op_sel:[1,0]
	v_mul_f32_e32 v118, v107, v107
	v_mov_b32_e32 v119, v135
	v_mov_b32_e32 v111, v134
	v_pk_mul_f32 v[102:103], v[102:103], v[96:97]
	v_pk_add_f32 v[96:97], v[84:85], v[96:97]
	v_mov_b32_e32 v106, v89
	v_pk_add_f32 v[110:111], v[118:119], v[110:111]
	v_mov_b32_e32 v103, v97
	v_pk_add_f32 v[96:97], v[102:103], v[110:111]
	v_pk_mul_f32 v[102:103], v[106:107], v[98:99]
	v_pk_add_f32 v[98:99], v[106:107], v[98:99]
	s_waitcnt vmcnt(15)
	v_and_b32_e32 v136, 0xffff0000, v93
	v_mov_b32_e32 v103, v99
	v_lshlrev_b32_e32 v137, 16, v93
	v_pk_add_f32 v[96:97], v[102:103], v[96:97]
	v_pk_mul_f32 v[98:99], v[176:177], v[176:177]
	v_pk_add_f32 v[102:103], v[176:177], v[88:89] op_sel_hi:[0,1]
	v_lshlrev_b32_e32 v85, 16, v92
	v_and_b32_e32 v93, 0xffff0000, v92
	v_mov_b32_e32 v99, v103
	v_mov_b32_e32 v102, v85
	v_mov_b32_e32 v103, v93
	v_mul_f32_e32 v106, v93, v93
	v_pk_fma_f32 v[102:103], v[102:103], v[102:103], v[106:107] op_sel_hi:[1,1,0]
	v_mul_f32_e32 v106, v137, v137
	v_pk_add_f32 v[96:97], v[98:99], v[96:97]
	v_and_b32_e32 v98, 0xffff0000, v94
	v_pk_add_f32 v[102:103], v[106:107], v[102:103] op_sel_hi:[0,1]
	v_pk_add_f32 v[96:97], v[100:101], v[96:97]
	v_and_b32_e32 v99, 16, v92
	v_mov_b32_e32 v92, v98
	v_lshlrev_b32_e32 v101, 16, v94
	v_lshlrev_b32_e32 v89, 16, v95
	v_pk_fma_f32 v[102:103], v[136:137], v[136:137], v[102:103]
	v_and_b32_e32 v176, 0xffff0000, v95
	v_pk_mov_b32 v[94:95], v[88:89], v[98:99] op_sel:[1,0]
	v_mul_f32_e32 v106, v101, v101
	v_mov_b32_e32 v107, v137
	v_mov_b32_e32 v103, v136
	v_pk_mul_f32 v[98:99], v[98:99], v[92:93]
	v_pk_add_f32 v[92:93], v[84:85], v[92:93]
	v_mov_b32_e32 v100, v89
	v_pk_add_f32 v[102:103], v[106:107], v[102:103]
	v_mov_b32_e32 v99, v93
	v_pk_add_f32 v[92:93], v[98:99], v[102:103]
	v_pk_mul_f32 v[98:99], v[100:101], v[94:95]
	v_pk_add_f32 v[94:95], v[100:101], v[94:95]
	v_lshlrev_b32_e32 v85, 16, v88
	v_mov_b32_e32 v99, v95
	v_pk_add_f32 v[92:93], v[98:99], v[92:93]
	v_pk_mul_f32 v[94:95], v[176:177], v[176:177]
	v_pk_add_f32 v[98:99], v[176:177], v[88:89] op_sel_hi:[0,1]
	v_mov_b32_e32 v95, v99
	v_pk_add_f32 v[92:93], v[94:95], v[92:93]
	v_and_b32_e32 v95, 16, v88
	v_and_b32_e32 v94, 0xffff0000, v90
	v_and_b32_e32 v89, 0xffff0000, v88
	v_lshlrev_b32_e32 v99, 16, v91
	v_pk_add_f32 v[92:93], v[96:97], v[92:93]
	v_lshlrev_b32_e32 v97, 16, v90
	v_and_b32_e32 v176, 0xffff0000, v91
	v_pk_mov_b32 v[90:91], v[98:99], v[94:95] op_sel:[1,0]
	v_mov_b32_e32 v100, v85
	v_mov_b32_e32 v101, v89
	v_mul_f32_e32 v98, v89, v89
; __device__ __forceinline__ void unpack8(const u32x4& w, f32x4& v0, f32x4& v1) { v0[0] = bflo(w.x); v0[1] = bfhi(w.x); v0[2] = bflo(w.y); v0[3] = bfhi(w.y); v1[0] = bflo(w.z); v1[1] = bfhi(w.z); v1[2] = bflo(w.w); v1[3] = bfhi(w.w); }
; __device__ __forceinline__ void sg_item(const Bufs& B, int l, int s, int it, unsigned char* shm) {
;     ...
;         float sum = 0.f, sq = 0.f;
; #pragma unroll
;         for (int i = 0; i < 16; ++i) { f32x4 a, bb; unpack8(sv[i], a, bb);
;             sum += (a[0] + a[1]) + (a[2] + a[3]) + (bb[0] + bb[1]) + (bb[2] + bb[3]);
;             sq += a[0] * a[0] + a[1] * a[1] + a[2] * a[2] + a[3] * a[3] + bb[0] * bb[0] + bb[1] * bb[1] + bb[2] * bb[2] + bb[3] * bb[3]; }
	v_pk_fma_f32 v[100:101], v[100:101], v[100:101], v[98:99] op_sel_hi:[1,1,0]
	v_mul_f32_e32 v98, v109, v109
	v_pk_add_f32 v[100:101], v[98:99], v[100:101] op_sel_hi:[0,1]
	v_mov_b32_e32 v88, v94
	v_pk_fma_f32 v[100:101], v[108:109], v[108:109], v[100:101]
	v_mul_f32_e32 v102, v97, v97
	v_mov_b32_e32 v103, v109
	v_mov_b32_e32 v101, v108
	v_pk_mul_f32 v[94:95], v[94:95], v[88:89]
	v_pk_add_f32 v[88:89], v[84:85], v[88:89]
	v_mov_b32_e32 v96, v99
	v_pk_add_f32 v[100:101], v[102:103], v[100:101]
	v_mov_b32_e32 v95, v89
	v_pk_add_f32 v[88:89], v[94:95], v[100:101]
	v_pk_mul_f32 v[94:95], v[96:97], v[90:91]
	v_pk_add_f32 v[90:91], v[96:97], v[90:91]
	v_lshlrev_b32_e32 v85, 16, v84
	v_mov_b32_e32 v95, v91
	v_pk_add_f32 v[88:89], v[94:95], v[88:89]
	v_pk_mul_f32 v[90:91], v[176:177], v[176:177]
	v_pk_add_f32 v[94:95], v[176:177], v[98:99] op_sel_hi:[0,1]
	v_mov_b32_e32 v91, v95
	v_pk_add_f32 v[88:89], v[90:91], v[88:89]
	v_and_b32_e32 v91, 16, v84
	v_pk_add_f32 v[88:89], v[92:93], v[88:89]
	v_and_b32_e32 v93, 0xffff0000, v84
	v_mov_b32_e32 v98, v85
	v_mov_b32_e32 v99, v93
	v_mul_f32_e32 v84, v93, v93
	v_pk_fma_f32 v[98:99], v[98:99], v[98:99], v[84:85] op_sel_hi:[1,1,0]
	v_mul_f32_e32 v84, v105, v105
	v_and_b32_e32 v90, 0xffff0000, v86
	v_pk_add_f32 v[98:99], v[84:85], v[98:99] op_sel_hi:[0,1]
	v_mov_b32_e32 v92, v90
	v_lshlrev_b32_e32 v95, 16, v86
	v_lshlrev_b32_e32 v97, 16, v87
	v_pk_fma_f32 v[98:99], v[104:105], v[104:105], v[98:99]
	v_and_b32_e32 v176, 0xffff0000, v87
	v_pk_mov_b32 v[86:87], v[96:97], v[90:91] op_sel:[1,0]
	v_mul_f32_e32 v100, v95, v95
	v_mov_b32_e32 v101, v105
	v_mov_b32_e32 v99, v104
	v_pk_mul_f32 v[90:91], v[90:91], v[92:93]
	v_pk_add_f32 v[84:85], v[84:85], v[92:93]
	v_mov_b32_e32 v94, v97
	v_pk_add_f32 v[98:99], v[100:101], v[98:99]
	v_mov_b32_e32 v91, v85
	v_pk_add_f32 v[84:85], v[90:91], v[98:99]
	v_pk_mul_f32 v[90:91], v[94:95], v[86:87]
	v_pk_add_f32 v[86:87], v[94:95], v[86:87]
	v_lshlrev_b32_e32 v93, 16, v82
	v_mov_b32_e32 v91, v87
	v_pk_add_f32 v[84:85], v[90:91], v[84:85]
	v_pk_mul_f32 v[86:87], v[176:177], v[176:177]
	v_pk_add_f32 v[90:91], v[176:177], v[96:97] op_sel_hi:[0,1]
	v_mov_b32_e32 v87, v91
	v_pk_add_f32 v[84:85], v[86:87], v[84:85]
	v_and_b32_e32 v86, 0xffff0000, v81
	v_lshlrev_b32_e32 v87, 16, v81
	v_lshlrev_b32_e32 v81, 16, v80
	v_and_b32_e32 v91, 0xffff0000, v80
	v_pk_add_f32 v[84:85], v[88:89], v[84:85]
	v_and_b32_e32 v89, 16, v80
	v_mov_b32_e32 v96, v81
	v_mov_b32_e32 v97, v91
	v_mul_f32_e32 v80, v91, v91
	v_pk_fma_f32 v[96:97], v[96:97], v[96:97], v[80:81] op_sel_hi:[1,1,0]
	v_mul_f32_e32 v80, v87, v87
	v_and_b32_e32 v88, 0xffff0000, v82
	v_pk_add_f32 v[96:97], v[80:81], v[96:97] op_sel_hi:[0,1]
	v_mov_b32_e32 v90, v88
	v_lshlrev_b32_e32 v95, 16, v83
	v_pk_fma_f32 v[96:97], v[86:87], v[86:87], v[96:97]
	v_and_b32_e32 v176, 0xffff0000, v83
	v_pk_mov_b32 v[82:83], v[94:95], v[88:89] op_sel:[1,0]
	v_mul_f32_e32 v98, v93, v93
	v_mov_b32_e32 v99, v87
	v_mov_b32_e32 v97, v86
	v_pk_mul_f32 v[88:89], v[88:89], v[90:91]
	v_pk_add_f32 v[80:81], v[80:81], v[90:91]
	v_mov_b32_e32 v92, v95
	v_pk_add_f32 v[86:87], v[98:99], v[96:97]
	v_mov_b32_e32 v89, v81
	v_pk_add_f32 v[80:81], v[88:89], v[86:87]
	v_pk_mul_f32 v[86:87], v[92:93], v[82:83]
	v_pk_add_f32 v[82:83], v[92:93], v[82:83]
	s_waitcnt vmcnt(11)
	v_and_b32_e32 v89, 0xffff0000, v76
	v_mov_b32_e32 v87, v83
	v_pk_add_f32 v[80:81], v[86:87], v[80:81]
	v_pk_mul_f32 v[82:83], v[176:177], v[176:177]
	v_pk_add_f32 v[86:87], v[176:177], v[94:95] op_sel_hi:[0,1]
	v_mov_b32_e32 v83, v87
	v_pk_add_f32 v[80:81], v[82:83], v[80:81]
	v_and_b32_e32 v82, 0xffff0000, v77
	v_lshlrev_b32_e32 v83, 16, v77
	v_lshlrev_b32_e32 v77, 16, v76
	v_and_b32_e32 v87, 16, v76
	v_mov_b32_e32 v94, v77
	v_mov_b32_e32 v95, v89
	v_mul_f32_e32 v76, v89, v89
	v_pk_fma_f32 v[94:95], v[94:95], v[94:95], v[76:77] op_sel_hi:[1,1,0]
	v_mul_f32_e32 v76, v83, v83
	v_and_b32_e32 v86, 0xffff0000, v78
	v_pk_add_f32 v[94:95], v[76:77], v[94:95] op_sel_hi:[0,1]
	v_and_b32_e32 v98, 0xffff0000, v79
	v_mov_b32_e32 v88, v86
	v_lshlrev_b32_e32 v79, 16, v79
	v_lshlrev_b32_e32 v91, 16, v78
	v_pk_fma_f32 v[94:95], v[82:83], v[82:83], v[94:95]
	v_pk_mov_b32 v[92:93], v[78:79], v[86:87] op_sel:[1,0]
	v_mul_f32_e32 v96, v91, v91
	v_mov_b32_e32 v97, v83
	v_mov_b32_e32 v95, v82
	v_pk_mul_f32 v[86:87], v[86:87], v[88:89]
	v_pk_add_f32 v[76:77], v[76:77], v[88:89]
	v_mov_b32_e32 v90, v79
	v_pk_add_f32 v[82:83], v[96:97], v[94:95]
	v_mov_b32_e32 v87, v77
	v_pk_add_f32 v[76:77], v[86:87], v[82:83]
	v_pk_mul_f32 v[82:83], v[90:91], v[92:93]
	v_pk_add_f32 v[86:87], v[90:91], v[92:93]
	v_and_b32_e32 v89, 0xffff0000, v72
	v_mov_b32_e32 v83, v87
	v_pk_add_f32 v[76:77], v[82:83], v[76:77]
	v_and_b32_e32 v82, 0xffff0000, v73
	v_lshlrev_b32_e32 v83, 16, v73
	v_lshlrev_b32_e32 v73, 16, v72
	v_and_b32_e32 v87, 16, v72
	v_and_b32_e32 v86, 0xffff0000, v74
	v_mov_b32_e32 v90, v73
	v_mov_b32_e32 v91, v89
	v_mul_f32_e32 v72, v89, v89
	v_mov_b32_e32 v88, v86
	v_pk_fma_f32 v[90:91], v[90:91], v[90:91], v[72:73] op_sel_hi:[1,1,0]
	v_mul_f32_e32 v72, v83, v83
	v_pk_add_f32 v[90:91], v[72:73], v[90:91] op_sel_hi:[0,1]
	v_pk_mul_f32 v[92:93], v[86:87], v[88:89]
	v_pk_add_f32 v[72:73], v[72:73], v[88:89]
	v_pk_fma_f32 v[90:91], v[82:83], v[82:83], v[90:91]
	v_mov_b32_e32 v93, v73
	v_lshlrev_b32_e32 v73, 16, v75
	v_lshlrev_b32_e32 v72, 16, v74
	v_pk_mul_f32 v[88:89], v[72:73], v[72:73]
	v_mov_b32_e32 v91, v82
	v_mov_b32_e32 v82, v88
	v_pk_add_f32 v[82:83], v[82:83], v[90:91]
	v_and_b32_e32 v91, 0xffff0000, v68
	v_lshlrev_b32_e32 v90, 16, v68
	v_mul_f32_e32 v68, v91, v91
	v_and_b32_e32 v94, 0xffff0000, v75
	v_pk_add_f32 v[82:83], v[92:93], v[82:83]
; __device__ __forceinline__ void unpack8(const u32x4& w, f32x4& v0, f32x4& v1) { v0[0] = bflo(w.x); v0[1] = bfhi(w.x); v0[2] = bflo(w.y); v0[3] = bfhi(w.y); v1[0] = bflo(w.z); v1[1] = bfhi(w.z); v1[2] = bflo(w.w); v1[3] = bfhi(w.w); }
; __device__ __forceinline__ void sg_item(const Bufs& B, int l, int s, int it, unsigned char* shm) {
;     ...
;         float sum = 0.f, sq = 0.f;
; #pragma unroll
;         for (int i = 0; i < 16; ++i) { f32x4 a, bb; unpack8(sv[i], a, bb);
;             sum += (a[0] + a[1]) + (a[2] + a[3]) + (bb[0] + bb[1]) + (bb[2] + bb[3]);
;             sq += a[0] * a[0] + a[1] * a[1] + a[2] * a[2] + a[3] * a[3] + bb[0] * bb[0] + bb[1] * bb[1] + bb[2] * bb[2] + bb[3] * bb[3]; }
;         sum += __shfl_xor(sum, 1); sum += __shfl_xor(sum, 2); sq += __shfl_xor(sq, 1); sq += __shfl_xor(sq, 2);
;         const float mean = sum * (1.0f / 512.0f), var = sq * (1.0f / 512.0f) - mean * mean, rstd = rsqrtf(fmaxf(var, 0.f) + 1e-5f);
; #pragma unroll
;         for (int i = 0; i < 4; ++i) { const int idx = tid + 512 * i; uv[i] = *(const u32x4*)(B.bufC + (size_t)(m0 + (idx >> 4)) * 1024 + g * 128 + (idx & 15) * 8); }
	v_pk_add_f32 v[92:93], v[90:91], v[90:91] op_sel_hi:[0,1]
	v_pk_fma_f32 v[90:91], v[90:91], v[90:91], v[68:69] op_sel_hi:[1,1,0]
	v_and_b32_e32 v68, 0xffff0000, v69
	v_lshlrev_b32_e32 v69, 16, v69
	v_add_f32_e32 v75, v73, v94
	v_pk_add_f32 v[72:73], v[72:73], v[86:87]
	v_lshlrev_b32_e32 v87, 16, v71
	v_mul_f32_e32 v86, v69, v69
	v_pk_add_f32 v[90:91], v[86:87], v[90:91] op_sel_hi:[0,1]
	v_pk_mov_b32 v[72:73], v[88:89], v[72:73] op_sel:[1,0]
	v_lshlrev_b32_e32 v88, 16, v70
	v_pk_fma_f32 v[90:91], v[68:69], v[68:69], v[90:91]
	v_mul_f32_e32 v74, v94, v94
	v_and_b32_e32 v96, 0xffff0000, v70
	v_mul_f32_e32 v94, v88, v88
	v_mov_b32_e32 v95, v69
	v_mov_b32_e32 v91, v68
	v_and_b32_e32 v97, 0xffff0000, v64
	v_add_f32_e32 v89, v88, v96
	v_pk_add_f32 v[68:69], v[94:95], v[90:91]
	v_mul_f32_e32 v92, v96, v96
	v_lshlrev_b32_e32 v94, 16, v64
	v_and_b32_e32 v96, s0, v64
	v_mov_b32_e32 v95, v97
	v_mul_f32_e32 v64, v97, v97
	v_add_f32_e32 v79, v79, v98
	v_mul_f32_e32 v78, v98, v98
	v_pk_add_f32 v[98:99], v[94:95], v[96:97] op_sel_hi:[0,1]
	v_pk_fma_f32 v[94:95], v[94:95], v[94:95], v[64:65] op_sel_hi:[1,1,0]
	v_and_b32_e32 v64, 0xffff0000, v65
	v_lshlrev_b32_e32 v65, 16, v65
	v_and_b32_e32 v70, 0xffff0000, v71
	v_lshlrev_b32_e32 v91, 16, v66
	v_and_b32_e32 v71, 0xffff0000, v66
	v_lshlrev_b32_e32 v90, 16, v67
	v_and_b32_e32 v66, 0xffff0000, v67
	v_mul_f32_e32 v86, v65, v65
	s_waitcnt vmcnt(7)
	v_lshlrev_b32_e32 v97, 16, v60
	v_and_b32_e32 v67, 0xffff0000, v60
	v_and_b32_e32 v100, 0xffff0000, v61
	v_lshlrev_b32_e32 v101, 16, v61
	v_and_b32_e32 v60, 0xffff0000, v49
	v_lshlrev_b32_e32 v61, 16, v49
	v_cndmask_b32_e32 v49, v204, v206, vcc
	v_pk_add_f32 v[80:81], v[84:85], v[80:81]
	v_pk_add_f32 v[76:77], v[78:79], v[76:77]
	v_pk_add_f32 v[72:73], v[72:73], v[82:83]
	v_pk_add_f32 v[94:95], v[86:87], v[94:95] op_sel_hi:[0,1]
	v_lshlrev_b32_e32 v86, 2, v49
	v_pk_add_f32 v[76:77], v[80:81], v[76:77]
	v_pk_add_f32 v[72:73], v[74:75], v[72:73]
	v_pk_add_f32 v[68:69], v[92:93], v[68:69]
	v_pk_add_f32 v[72:73], v[76:77], v[72:73]
	v_mul_f32_e32 v88, v87, v87
	v_pk_add_f32 v[76:77], v[70:71], v[86:87] op_sel_hi:[0,1]
	v_pk_add_f32 v[68:69], v[88:89], v[68:69]
	v_mul_f32_e32 v74, v70, v70
	v_mov_b32_e32 v75, v77
	v_pk_add_f32 v[68:69], v[74:75], v[68:69]
	v_pk_fma_f32 v[94:95], v[64:65], v[64:65], v[94:95]
	v_pk_add_f32 v[68:69], v[72:73], v[68:69]
	v_pk_mul_f32 v[72:73], v[90:91], v[90:91]
	v_mov_b32_e32 v70, v90
	v_mov_b32_e32 v72, v73
	v_mov_b32_e32 v73, v65
	v_mov_b32_e32 v95, v64
	v_cmp_lt_i32_e32 vcc, v207, v205
	v_pk_add_f32 v[64:65], v[72:73], v[94:95]
	v_pk_mul_f32 v[72:73], v[70:71], v[70:71]
	v_cndmask_b32_e32 v49, v204, v207, vcc
	v_mov_b32_e32 v98, v73
	v_pk_add_f32 v[70:71], v[90:91], v[70:71]
	v_lshlrev_b32_e32 v108, 2, v49
	v_mov_b32_e32 v49, v90
	v_pk_add_f32 v[64:65], v[98:99], v[64:65]
	v_mul_f32_e32 v72, v90, v90
	v_mov_b32_e32 v73, v71
	v_pk_add_f32 v[64:65], v[72:73], v[64:65]
	v_pk_add_f32 v[72:73], v[66:67], v[48:49] op_sel_hi:[0,1]
	v_mul_f32_e32 v70, v66, v66
	v_mov_b32_e32 v71, v73
	v_pk_add_f32 v[64:65], v[70:71], v[64:65]
	v_mov_b32_e32 v70, v97
	v_mov_b32_e32 v71, v67
	v_mul_f32_e32 v72, v67, v67
	v_pk_fma_f32 v[70:71], v[70:71], v[70:71], v[72:73] op_sel_hi:[1,1,0]
	v_mul_f32_e32 v72, v101, v101
	v_and_b32_e32 v96, 0xffff0000, v62
	v_pk_add_f32 v[70:71], v[72:73], v[70:71] op_sel_hi:[0,1]
	v_pk_add_f32 v[64:65], v[68:69], v[64:65]
	v_mov_b32_e32 v66, v96
	v_lshlrev_b32_e32 v69, 16, v62
	v_pk_fma_f32 v[70:71], v[100:101], v[100:101], v[70:71]
	v_lshlrev_b32_e32 v49, 16, v63
	v_mul_f32_e32 v72, v69, v69
	v_mov_b32_e32 v73, v101
	v_mov_b32_e32 v71, v100
	v_pk_add_f32 v[66:67], v[96:97], v[66:67]
	v_and_b32_e32 v176, 0xffff0000, v63
	v_mov_b32_e32 v68, v49
	v_pk_mov_b32 v[62:63], v[48:49], v[96:97] op_sel:[1,0]
	v_pk_add_f32 v[70:71], v[72:73], v[70:71]
	v_mul_f32_e32 v72, v96, v96
	v_mov_b32_e32 v73, v67
	v_pk_add_f32 v[66:67], v[72:73], v[70:71]
	v_pk_mul_f32 v[70:71], v[68:69], v[62:63]
	v_pk_add_f32 v[62:63], v[68:69], v[62:63]
	v_pk_add_f32 v[68:69], v[176:177], v[48:49] op_sel_hi:[0,1]
	v_mov_b32_e32 v71, v63
	v_pk_add_f32 v[62:63], v[70:71], v[66:67]
	v_pk_mul_f32 v[66:67], v[176:177], v[176:177]
	v_lshlrev_b32_e32 v103, 16, v56
	v_and_b32_e32 v104, 0xffff0000, v57
	v_lshlrev_b32_e32 v105, 16, v57
	v_mov_b32_e32 v67, v69
	v_and_b32_e32 v57, 0xffff0000, v56
	v_pk_add_f32 v[62:63], v[66:67], v[62:63]
	v_mov_b32_e32 v66, v103
	v_mov_b32_e32 v67, v57
	v_mul_f32_e32 v68, v57, v57
	v_pk_fma_f32 v[66:67], v[66:67], v[66:67], v[68:69] op_sel_hi:[1,1,0]
	v_mul_f32_e32 v68, v105, v105
	v_pk_add_f32 v[66:67], v[68:69], v[66:67] op_sel_hi:[0,1]
	v_pk_add_f32 v[62:63], v[64:65], v[62:63]
	v_and_b32_e32 v56, 0xffff0000, v58
	v_lshlrev_b32_e32 v65, 16, v58
	v_pk_fma_f32 v[66:67], v[104:105], v[104:105], v[66:67]
	v_mov_b32_e32 v102, v56
	v_lshlrev_b32_e32 v49, 16, v59
	v_mul_f32_e32 v68, v65, v65
	v_mov_b32_e32 v69, v105
	v_mov_b32_e32 v67, v104
	v_and_b32_e32 v176, 0xffff0000, v59
	v_pk_mov_b32 v[58:59], v[48:49], v[56:57] op_sel:[1,0]
	v_pk_add_f32 v[66:67], v[68:69], v[66:67]
	v_pk_mul_f32 v[68:69], v[56:57], v[56:57]
	v_pk_add_f32 v[56:57], v[102:103], v[56:57]
	v_mov_b32_e32 v64, v49
	v_mov_b32_e32 v69, v57
	v_pk_add_f32 v[56:57], v[68:69], v[66:67]
	v_pk_mul_f32 v[66:67], v[64:65], v[58:59]
	v_pk_add_f32 v[58:59], v[64:65], v[58:59]
	v_pk_add_f32 v[64:65], v[176:177], v[48:49] op_sel_hi:[0,1]
	v_mov_b32_e32 v67, v59
	v_pk_mul_f32 v[58:59], v[176:177], v[176:177]
	v_pk_add_f32 v[56:57], v[66:67], v[56:57]
	v_mov_b32_e32 v59, v65
	v_and_b32_e32 v106, 0xffff0000, v53
	v_lshlrev_b32_e32 v107, 16, v53
	v_pk_add_f32 v[56:57], v[58:59], v[56:57]
; __device__ __forceinline__ void unpack8(const u32x4& w, f32x4& v0, f32x4& v1) { v0[0] = bflo(w.x); v0[1] = bfhi(w.x); v0[2] = bflo(w.y); v0[3] = bfhi(w.y); v1[0] = bflo(w.z); v1[1] = bfhi(w.z); v1[2] = bflo(w.w); v1[3] = bfhi(w.w); }
; __device__ __forceinline__ void sg_item(const Bufs& B, int l, int s, int it, unsigned char* shm) {
;     ...
;         float sum = 0.f, sq = 0.f;
; #pragma unroll
;         for (int i = 0; i < 16; ++i) { f32x4 a, bb; unpack8(sv[i], a, bb);
;             sum += (a[0] + a[1]) + (a[2] + a[3]) + (bb[0] + bb[1]) + (bb[2] + bb[3]);
;             sq += a[0] * a[0] + a[1] * a[1] + a[2] * a[2] + a[3] * a[3] + bb[0] * bb[0] + bb[1] * bb[1] + bb[2] * bb[2] + bb[3] * bb[3]; }
;         sum += __shfl_xor(sum, 1); sum += __shfl_xor(sum, 2); sq += __shfl_xor(sq, 1); sq += __shfl_xor(sq, 2);
;         const float mean = sum * (1.0f / 512.0f), var = sq * (1.0f / 512.0f) - mean * mean, rstd = rsqrtf(fmaxf(var, 0.f) + 1e-5f);
; #pragma unroll
;         for (int i = 0; i < 4; ++i) { const int idx = tid + 512 * i; uv[i] = *(const u32x4*)(B.bufC + (size_t)(m0 + (idx >> 4)) * 1024 + g * 128 + (idx & 15) * 8); }
	v_and_b32_e32 v59, 16, v52
	v_and_b32_e32 v58, 0xffff0000, v54
	v_lshlrev_b32_e32 v49, 16, v52
	v_and_b32_e32 v53, 0xffff0000, v52
	v_lshlrev_b32_e32 v65, 16, v55
	v_pk_add_f32 v[56:57], v[62:63], v[56:57]
	v_lshlrev_b32_e32 v63, 16, v54
	v_and_b32_e32 v176, 0xffff0000, v55
	v_pk_mov_b32 v[54:55], v[64:65], v[58:59] op_sel:[1,0]
	v_mov_b32_e32 v66, v49
	v_mov_b32_e32 v67, v53
	v_mul_f32_e32 v64, v53, v53
	v_pk_fma_f32 v[66:67], v[66:67], v[66:67], v[64:65] op_sel_hi:[1,1,0]
	v_mul_f32_e32 v64, v107, v107
	v_pk_add_f32 v[66:67], v[64:65], v[66:67] op_sel_hi:[0,1]
	v_mov_b32_e32 v52, v58
	v_pk_fma_f32 v[66:67], v[106:107], v[106:107], v[66:67]
	v_mul_f32_e32 v68, v63, v63
	v_mov_b32_e32 v69, v107
	v_mov_b32_e32 v67, v106
	v_pk_mul_f32 v[58:59], v[58:59], v[52:53]
	v_pk_add_f32 v[52:53], v[48:49], v[52:53]
	v_mov_b32_e32 v62, v65
	v_pk_add_f32 v[66:67], v[68:69], v[66:67]
	v_mov_b32_e32 v59, v53
	v_pk_add_f32 v[52:53], v[58:59], v[66:67]
	v_pk_mul_f32 v[58:59], v[62:63], v[54:55]
	v_pk_add_f32 v[54:55], v[62:63], v[54:55]
	v_lshlrev_b32_e32 v49, 16, v48
	v_mov_b32_e32 v59, v55
	v_pk_add_f32 v[52:53], v[58:59], v[52:53]
	v_pk_mul_f32 v[54:55], v[176:177], v[176:177]
	v_pk_add_f32 v[58:59], v[176:177], v[64:65] op_sel_hi:[0,1]
	v_mov_b32_e32 v55, v59
	v_pk_add_f32 v[52:53], v[54:55], v[52:53]
	v_and_b32_e32 v55, 16, v48
	v_pk_add_f32 v[52:53], v[56:57], v[52:53]
	v_and_b32_e32 v57, 0xffff0000, v48
	v_mov_b32_e32 v64, v49
	v_mov_b32_e32 v65, v57
	v_mul_f32_e32 v48, v57, v57
	v_pk_fma_f32 v[64:65], v[64:65], v[64:65], v[48:49] op_sel_hi:[1,1,0]
	v_mul_f32_e32 v48, v61, v61
	v_and_b32_e32 v54, 0xffff0000, v50
	v_pk_add_f32 v[64:65], v[48:49], v[64:65] op_sel_hi:[0,1]
	v_mov_b32_e32 v56, v54
	v_lshlrev_b32_e32 v59, 16, v50
	v_lshlrev_b32_e32 v63, 16, v51
	v_pk_fma_f32 v[64:65], v[60:61], v[60:61], v[64:65]
	v_and_b32_e32 v176, 0xffff0000, v51
	v_pk_mov_b32 v[50:51], v[62:63], v[54:55] op_sel:[1,0]
	v_mul_f32_e32 v66, v59, v59
	v_mov_b32_e32 v67, v61
	v_mov_b32_e32 v65, v60
	v_pk_mul_f32 v[54:55], v[54:55], v[56:57]
	v_pk_add_f32 v[48:49], v[48:49], v[56:57]
	v_mov_b32_e32 v58, v63
	v_pk_add_f32 v[60:61], v[66:67], v[64:65]
	v_mov_b32_e32 v55, v49
	v_pk_add_f32 v[48:49], v[54:55], v[60:61]
	v_pk_mul_f32 v[54:55], v[58:59], v[50:51]
	v_pk_add_f32 v[50:51], v[58:59], v[50:51]
	v_add_u32_e32 v99, 0x200, v114
	v_mov_b32_e32 v55, v51
	v_pk_add_f32 v[48:49], v[54:55], v[48:49]
	v_pk_mul_f32 v[50:51], v[176:177], v[176:177]
	v_pk_add_f32 v[54:55], v[176:177], v[62:63] op_sel_hi:[0,1]
	v_mov_b32_e32 v51, v55
	v_pk_add_f32 v[48:49], v[50:51], v[48:49]
	v_add_u32_e32 v98, 0x400, v114
	v_pk_add_f32 v[48:49], v[52:53], v[48:49]
	ds_bpermute_b32 v51, v86, v49
	ds_bpermute_b32 v50, v86, v48
	v_add_u32_e32 v97, 0x600, v114
	v_ashrrev_i32_e32 v94, 4, v99
	v_ashrrev_i32_e32 v95, 4, v98
	v_ashrrev_i32_e32 v96, 4, v97
	s_waitcnt lgkmcnt(0)
	v_pk_add_f32 v[48:49], v[48:49], v[50:51]
	ds_bpermute_b32 v51, v108, v49
	ds_bpermute_b32 v50, v108, v48
	v_add_u32_e32 v52, s38, v94
	v_add_u32_e32 v56, s38, v95
	v_add_u32_e32 v62, s38, v96
	v_ashrrev_i32_e32 v53, 31, v52
	s_waitcnt lgkmcnt(0)
	v_pk_add_f32 v[48:49], v[48:49], v[50:51]
	v_ashrrev_i32_e32 v57, 31, v56
	v_pk_mul_f32 v[92:93], v[48:49], s[2:3] op_sel_hi:[1,0]
	s_lshl_b32 s2, s20, 8
	v_fma_f32 v48, -v93, v93, v92
	v_max_f32_e32 v48, 0, v48
	v_add_f32_e32 v48, 0x3727c5ac, v48
	v_cmp_gt_f32_e32 vcc, s33, v48
	v_mul_f32_e32 v49, 0x4b800000, v48
	v_ashrrev_i32_e32 v92, 4, v114
	v_cndmask_b32_e32 v48, v48, v49, vcc
	v_rsq_f32_e32 v64, v48
	v_lshlrev_b32_e32 v48, 4, v114
	s_add_u32 s2, s16, s2
	v_and_b32_e32 v176, 0xf0, v48
	v_add_u32_e32 v48, s38, v92
	s_addc_u32 s3, s17, 0
	v_ashrrev_i32_e32 v49, 31, v48
	v_ashrrev_i32_e32 v63, 31, v62
	v_lshl_add_u64 v[60:61], s[2:3], 0, v[176:177]
	v_lshlrev_b64 v[48:49], 11, v[48:49]
	v_lshlrev_b64 v[52:53], 11, v[52:53]
	v_lshlrev_b64 v[56:57], 11, v[56:57]
	v_lshlrev_b64 v[62:63], 11, v[62:63]
	v_lshl_add_u64 v[48:49], v[60:61], 0, v[48:49]
	v_lshl_add_u64 v[52:53], v[60:61], 0, v[52:53]
	v_lshl_add_u64 v[56:57], v[60:61], 0, v[56:57]
	v_lshl_add_u64 v[60:61], v[60:61], 0, v[62:63]
	global_load_dwordx4 v[16:19], v[16:17], off
	v_mul_f32_e32 v65, 0x45800000, v64
	global_load_dwordx4 v[20:23], v[20:21], off
	v_cndmask_b32_e32 v100, v64, v65, vcc
	global_load_dwordx4 v[24:27], v[24:25], off
	s_waitcnt vmcnt(6)
	v_lshlrev_b32_e32 v64, 16, v44
	global_load_dwordx4 v[28:31], v[28:29], off
	v_lshlrev_b32_e32 v101, 2, v117
	global_load_dwordx4 v[32:35], v[32:33], off
	s_barrier
; __device__ __forceinline__ bf16_t f2bf(float f) { unsigned u = __float_as_uint(f); u += 0x7FFFu + ((u >> 16) & 1u); return (bf16_t)(u >> 16); }
; __device__ __forceinline__ void unpack8(const u32x4& w, f32x4& v0, f32x4& v1) { v0[0] = bflo(w.x); v0[1] = bfhi(w.x); v0[2] = bflo(w.y); v0[3] = bfhi(w.y); v1[0] = bflo(w.z); v1[1] = bfhi(w.z); v1[2] = bflo(w.w); v1[3] = bfhi(w.w); }
; __device__ __forceinline__ void sg_item(const Bufs& B, int l, int s, int it, unsigned char* shm) {
;     ...
;         const float* lnw = IN(17) + l * 512 + cg0; const float* lnb = IN(18) + l * 512 + cg0;
; #pragma unroll
;         for (int i = 0; i < 4; ++i) { f32x4 a, bb; unpack8(vq[i], a, bb);
; #pragma unroll
;             for (int j = 0; j < 4; ++j) {
;                 VnT[(cl0 + i * 8 + j) * 136 + t] = f2bf((a[j] - mean) * rstd * lnw[i * 8 + j] + lnb[i * 8 + j]);
;                 VnT[(cl0 + i * 8 + 4 + j) * 136 + t] = f2bf((bb[j] - mean) * rstd * lnw[i * 8 + 4 + j] + lnb[i * 8 + 4 + j]); } }
	global_load_dwordx4 v[48:51], v[48:49], off
	v_and_b32_e32 v103, 0xffff0000, v44
	global_load_dwordx4 v[52:55], v[52:53], off
	v_sub_f32_e32 v44, v64, v93
	global_load_dwordx4 v[56:59], v[56:57], off
	v_lshlrev_b32_e32 v104, 16, v45
	global_load_dwordx4 v[60:63], v[60:61], off
	s_load_dwordx2 s[2:3], s[0:1], 0x88
	s_waitcnt lgkmcnt(0)
	s_add_u32 s22, s2, s18
	s_addc_u32 s23, s3, s19
	s_load_dwordx2 s[2:3], s[0:1], 0x90
	s_waitcnt lgkmcnt(0)
	s_add_u32 s20, s2, s18
	s_addc_u32 s21, s3, s19
	v_and_b32_e32 v105, 0xffff0000, v45
	v_lshlrev_b32_e32 v106, 16, v46
	v_and_b32_e32 v107, 0xffff0000, v46
	v_lshlrev_b32_e32 v108, 16, v47
	v_and_b32_e32 v109, 0xffff0000, v47
	v_mul_f32_e32 v110, v44, v100
	global_load_dwordx4 v[44:47], v101, s[22:23] offset:48
	global_load_dwordx4 v[64:67], v101, s[22:23] offset:32
	global_load_dwordx4 v[76:79], v101, s[22:23] offset:16
	global_load_dwordx4 v[84:87], v101, s[22:23]
	global_load_dwordx4 v[68:71], v101, s[20:21] offset:48
	global_load_dwordx4 v[72:75], v101, s[20:21] offset:32
	global_load_dwordx4 v[80:83], v101, s[20:21] offset:16
	global_load_dwordx4 v[88:91], v101, s[20:21]
	v_lshlrev_b32_e32 v102, 1, v116
	s_add_i32 s39, 0, 0x11000
	s_waitcnt vmcnt(0)
	v_fma_f32 v84, v84, v110, v88
	v_bfe_u32 v88, v84, 16, 1
	v_add3_u32 v88, v84, v88, s78
	v_mul_u32_u24_e32 v84, 0x1100, v115
	v_lshlrev_b32_e32 v110, 1, v84
	v_add3_u32 v84, 0, v102, v110
	ds_write_b16_d16_hi v84, v88 offset:34816
	v_sub_f32_e32 v88, v106, v93
	v_mul_f32_e32 v88, v88, v100
	v_fma_f32 v76, v76, v88, v80
	v_bfe_u32 v80, v76, 16, 1
	v_add3_u32 v76, v76, v80, s78
	v_add3_u32 v88, 0, v110, v102
	ds_write_b16_d16_hi v88, v76 offset:35904
	v_sub_f32_e32 v76, v103, v93
	v_mul_f32_e32 v76, v76, v100
	v_fma_f32 v76, v76, v85, v89
	v_bfe_u32 v80, v76, 16, 1
	v_add3_u32 v76, v76, v80, s78
	ds_write_b16_d16_hi v84, v76 offset:35088
	v_sub_f32_e32 v76, v107, v93
	v_mul_f32_e32 v76, v76, v100
	v_fma_f32 v76, v76, v77, v81
	v_bfe_u32 v77, v76, 16, 1
	v_add3_u32 v76, v76, v77, s78
	ds_write_b16_d16_hi v88, v76 offset:36176
	v_sub_f32_e32 v76, v104, v93
	v_mul_f32_e32 v76, v76, v100
	v_fma_f32 v76, v76, v86, v90
	v_bfe_u32 v77, v76, 16, 1
	v_add3_u32 v76, v76, v77, s78
	ds_write_b16_d16_hi v84, v76 offset:35360
	v_sub_f32_e32 v76, v108, v93
	v_mul_f32_e32 v76, v76, v100
	v_fma_f32 v76, v76, v78, v82
	v_bfe_u32 v77, v76, 16, 1
	v_add3_u32 v76, v76, v77, s78
	ds_write_b16_d16_hi v88, v76 offset:36448
	v_sub_f32_e32 v76, v105, v93
	v_mul_f32_e32 v76, v76, v100
	v_fmac_f32_e32 v91, v76, v87
	v_bfe_u32 v76, v91, 16, 1
	v_add3_u32 v76, v91, v76, s78
	ds_write_b16_d16_hi v84, v76 offset:35632
	v_sub_f32_e32 v76, v109, v93
	v_mul_f32_e32 v76, v76, v100
	v_fmac_f32_e32 v83, v76, v79
	v_bfe_u32 v76, v83, 16, 1
	v_add3_u32 v76, v83, v76, s78
	ds_write_b16_d16_hi v88, v76 offset:36720
	v_lshlrev_b32_e32 v76, 16, v40
	v_sub_f32_e32 v76, v76, v93
	v_mul_f32_e32 v76, v76, v100
	v_fma_f32 v64, v76, v64, v72
	v_bfe_u32 v72, v64, 16, 1
	v_lshlrev_b32_e32 v78, 16, v42
	v_add3_u32 v64, v64, v72, s78
	ds_write_b16_d16_hi v84, v64 offset:36992
	v_sub_f32_e32 v64, v78, v93
	v_and_b32_e32 v40, 0xffff0000, v40
	v_mul_f32_e32 v64, v64, v100
	v_fma_f32 v44, v64, v44, v68
	v_sub_f32_e32 v40, v40, v93
	v_bfe_u32 v64, v44, 16, 1
	v_mul_f32_e32 v40, v40, v100
	v_add3_u32 v44, v44, v64, s78
	v_fma_f32 v40, v40, v65, v73
	ds_write_b16_d16_hi v88, v44 offset:38080
	v_bfe_u32 v44, v40, 16, 1
	v_and_b32_e32 v42, 0xffff0000, v42
	v_add3_u32 v40, v40, v44, s78
	ds_write_b16_d16_hi v84, v40 offset:37264
	v_sub_f32_e32 v40, v42, v93
	v_mul_f32_e32 v40, v40, v100
	v_fma_f32 v40, v40, v45, v69
	v_bfe_u32 v42, v40, 16, 1
	v_lshlrev_b32_e32 v77, 16, v41
	v_add3_u32 v40, v40, v42, s78
	ds_write_b16_d16_hi v88, v40 offset:38352
	v_sub_f32_e32 v40, v77, v93
	v_mul_f32_e32 v40, v40, v100
	v_fma_f32 v40, v40, v66, v74
	v_bfe_u32 v42, v40, 16, 1
	v_lshlrev_b32_e32 v79, 16, v43
	v_add3_u32 v40, v40, v42, s78
	ds_write_b16_d16_hi v84, v40 offset:37536
	v_sub_f32_e32 v40, v79, v93
	v_mul_f32_e32 v40, v40, v100
	v_fma_f32 v40, v40, v46, v70
	v_bfe_u32 v42, v40, 16, 1
	v_and_b32_e32 v41, 0xffff0000, v41
	v_add3_u32 v40, v40, v42, s78
	ds_write_b16_d16_hi v88, v40 offset:38624
	v_sub_f32_e32 v40, v41, v93
	v_mul_f32_e32 v40, v40, v100
	v_fmac_f32_e32 v75, v40, v67
	v_bfe_u32 v40, v75, 16, 1
	v_and_b32_e32 v43, 0xffff0000, v43
	v_add3_u32 v40, v75, v40, s78
	ds_write_b16_d16_hi v84, v40 offset:37808
	v_sub_f32_e32 v40, v43, v93
	v_mul_f32_e32 v40, v40, v100
	v_fmac_f32_e32 v71, v40, v47
	v_bfe_u32 v40, v71, 16, 1
	v_add3_u32 v40, v71, v40, s78
	ds_write_b16_d16_hi v88, v40 offset:38896
	v_lshlrev_b32_e32 v40, 16, v36
	v_and_b32_e32 v91, 0xffff0000, v36
	v_sub_f32_e32 v36, v40, v93
	v_lshlrev_b32_e32 v89, 16, v37
	v_and_b32_e32 v86, 0xffff0000, v37
	v_lshlrev_b32_e32 v102, 16, v38
	v_and_b32_e32 v90, 0xffff0000, v38
	v_lshlrev_b32_e32 v87, 16, v39
	v_and_b32_e32 v85, 0xffff0000, v39
	v_mul_f32_e32 v103, v36, v100
	global_load_dwordx4 v[36:39], v101, s[22:23] offset:112
	global_load_dwordx4 v[40:43], v101, s[22:23] offset:96
	global_load_dwordx4 v[44:47], v101, s[22:23] offset:80
	global_load_dwordx4 v[76:79], v101, s[22:23] offset:64
	global_load_dwordx4 v[64:67], v101, s[20:21] offset:112
	global_load_dwordx4 v[68:71], v101, s[20:21] offset:96
	global_load_dwordx4 v[72:75], v101, s[20:21] offset:80
	global_load_dwordx4 v[80:83], v101, s[20:21] offset:64
	s_waitcnt vmcnt(0)
; __device__ __forceinline__ unsigned cvt_pk_bf16(float lo, float hi) { const f32x2 v = {lo, hi}; return __builtin_bit_cast(unsigned, __builtin_convertvector(v, bf16x2_t)); }
; __device__ __forceinline__ bf16_t f2bf(float f) { unsigned u = __float_as_uint(f); u += 0x7FFFu + ((u >> 16) & 1u); return (bf16_t)(u >> 16); }
; __device__ __forceinline__ void unpack8(const u32x4& w, f32x4& v0, f32x4& v1) { v0[0] = bflo(w.x); v0[1] = bfhi(w.x); v0[2] = bflo(w.y); v0[3] = bfhi(w.y); v1[0] = bflo(w.z); v1[1] = bfhi(w.z); v1[2] = bflo(w.w); v1[3] = bfhi(w.w); }
; __device__ __forceinline__ void sg_item(const Bufs& B, int l, int s, int it, unsigned char* shm) {
;     ...
;         for (int i = 0; i < 4; ++i) { f32x4 a, bb; unpack8(vq[i], a, bb);
; #pragma unroll
;             for (int j = 0; j < 4; ++j) {
;                 VnT[(cl0 + i * 8 + j) * 136 + t] = f2bf((a[j] - mean) * rstd * lnw[i * 8 + j] + lnb[i * 8 + j]);
;                 VnT[(cl0 + i * 8 + 4 + j) * 136 + t] = f2bf((bb[j] - mean) * rstd * lnw[i * 8 + 4 + j] + lnb[i * 8 + 4 + j]); } }
; #pragma unroll
;         for (int i = 0; i < 8; ++i) { const int idx = tid + 512 * i, tt = idx >> 5, s4 = (idx & 31) * 4;
;             u32x2 w; w.x = cvt_pk_bf16(s4 <= tt ? wv[i][0] : 0.f, s4 + 1 <= tt ? wv[i][1] : 0.f); w.y = cvt_pk_bf16(s4 + 2 <= tt ? wv[i][2] : 0.f, s4 + 3 <= tt ? wv[i][3] : 0.f);
;             *(u32x2*)(Wm + tt * 136 + s4) = w; }
	v_fma_f32 v76, v103, v76, v80
	v_bfe_u32 v80, v76, 16, 1
	v_add3_u32 v76, v76, v80, s78
	ds_write_b16_d16_hi v84, v76 offset:39168
	v_sub_f32_e32 v76, v102, v93
	v_mul_f32_e32 v76, v76, v100
	v_fma_f32 v44, v76, v44, v72
	v_bfe_u32 v72, v44, 16, 1
	v_add3_u32 v44, v44, v72, s78
	ds_write_b16_d16_hi v88, v44 offset:40256
	v_sub_f32_e32 v44, v91, v93
	v_mul_f32_e32 v44, v44, v100
	v_fma_f32 v44, v44, v77, v81
	v_bfe_u32 v72, v44, 16, 1
	v_add3_u32 v44, v44, v72, s78
	ds_write_b16_d16_hi v84, v44 offset:39440
	v_sub_f32_e32 v44, v90, v93
	v_mul_f32_e32 v44, v44, v100
	v_fma_f32 v44, v44, v45, v73
	v_bfe_u32 v45, v44, 16, 1
	v_add3_u32 v44, v44, v45, s78
	ds_write_b16_d16_hi v88, v44 offset:40528
	v_sub_f32_e32 v44, v89, v93
	v_mul_f32_e32 v44, v44, v100
	v_fma_f32 v44, v44, v78, v82
	v_bfe_u32 v45, v44, 16, 1
	v_add3_u32 v44, v44, v45, s78
	ds_write_b16_d16_hi v84, v44 offset:39712
	v_sub_f32_e32 v44, v87, v93
	v_mul_f32_e32 v44, v44, v100
	v_fma_f32 v44, v44, v46, v74
	v_bfe_u32 v45, v44, 16, 1
	v_add3_u32 v44, v44, v45, s78
	ds_write_b16_d16_hi v88, v44 offset:40800
	v_sub_f32_e32 v44, v86, v93
	v_mul_f32_e32 v44, v44, v100
	v_fmac_f32_e32 v83, v44, v79
	v_bfe_u32 v44, v83, 16, 1
	v_add3_u32 v44, v83, v44, s78
	ds_write_b16_d16_hi v84, v44 offset:39984
	v_sub_f32_e32 v44, v85, v93
	v_mul_f32_e32 v44, v44, v100
	v_fmac_f32_e32 v75, v44, v47
	v_bfe_u32 v44, v75, 16, 1
	v_add3_u32 v44, v75, v44, s78
	ds_write_b16_d16_hi v88, v44 offset:41072
	v_lshlrev_b32_e32 v44, 16, v0
	v_sub_f32_e32 v44, v44, v93
	v_mul_f32_e32 v44, v44, v100
	v_fma_f32 v40, v44, v40, v68
	v_bfe_u32 v44, v40, 16, 1
	v_lshlrev_b32_e32 v46, 16, v2
	v_add3_u32 v40, v40, v44, s78
	ds_write_b16_d16_hi v84, v40 offset:41344
	v_sub_f32_e32 v40, v46, v93
	v_and_b32_e32 v0, 0xffff0000, v0
	v_mul_f32_e32 v40, v40, v100
	v_fma_f32 v36, v40, v36, v64
	v_sub_f32_e32 v0, v0, v93
	v_bfe_u32 v40, v36, 16, 1
	v_mul_f32_e32 v0, v0, v100
	v_add3_u32 v36, v36, v40, s78
	v_fma_f32 v0, v0, v41, v69
	ds_write_b16_d16_hi v88, v36 offset:42432
	v_bfe_u32 v36, v0, 16, 1
	v_and_b32_e32 v2, 0xffff0000, v2
	v_add3_u32 v0, v0, v36, s78
	ds_write_b16_d16_hi v84, v0 offset:41616
	v_sub_f32_e32 v0, v2, v93
	v_mul_f32_e32 v0, v0, v100
	v_fma_f32 v0, v0, v37, v65
	v_bfe_u32 v2, v0, 16, 1
	v_lshlrev_b32_e32 v45, 16, v1
	v_add3_u32 v0, v0, v2, s78
	ds_write_b16_d16_hi v88, v0 offset:42704
	v_sub_f32_e32 v0, v45, v93
	v_mul_f32_e32 v0, v0, v100
	v_fma_f32 v0, v0, v42, v70
	v_bfe_u32 v2, v0, 16, 1
	v_lshlrev_b32_e32 v47, 16, v3
	v_add3_u32 v0, v0, v2, s78
	ds_write_b16_d16_hi v84, v0 offset:41888
	v_sub_f32_e32 v0, v47, v93
	v_mul_f32_e32 v0, v0, v100
	v_fma_f32 v0, v0, v38, v66
	v_bfe_u32 v2, v0, 16, 1
	v_and_b32_e32 v1, 0xffff0000, v1
	v_add3_u32 v0, v0, v2, s78
	ds_write_b16_d16_hi v88, v0 offset:42976
	v_sub_f32_e32 v0, v1, v93
	v_mul_f32_e32 v0, v0, v100
	v_fmac_f32_e32 v71, v0, v43
	v_bfe_u32 v0, v71, 16, 1
	v_and_b32_e32 v3, 0xffff0000, v3
	v_add3_u32 v0, v71, v0, s78
	ds_write_b16_d16_hi v84, v0 offset:42160
	v_sub_f32_e32 v0, v3, v93
	v_and_b32_e32 v1, 0x7c, v112
	v_ashrrev_i32_e32 v38, 5, v114
	v_mul_f32_e32 v0, v0, v100
	v_cmp_le_i32_e32 vcc, v1, v38
	v_fmac_f32_e32 v67, v0, v39
	v_or_b32_e32 v36, 2, v1
	v_cndmask_b32_e32 v2, 0, v8, vcc
	v_cmp_lt_i32_e32 vcc, v1, v38
	v_bfe_u32 v0, v67, 16, 1
	v_or_b32_e32 v37, 3, v1
	v_cndmask_b32_e32 v3, 0, v9, vcc
	v_cmp_le_i32_e32 vcc, v36, v38
	v_add3_u32 v0, v67, v0, s78
	v_cvt_pk_bf16_f32 v2, v2, v3
	v_cndmask_b32_e32 v3, 0, v10, vcc
	v_cmp_le_i32_e32 vcc, v37, v38
	ds_write_b16_d16_hi v88, v0 offset:43248
	v_lshl_add_u32 v0, v1, 1, 0
	v_cndmask_b32_e32 v8, 0, v11, vcc
	v_cvt_pk_bf16_f32 v3, v3, v8
	v_mad_u64_u32 v[8:9], s[2:3], v38, s77, v[0:1]
	ds_write_b64 v8, v[2:3]
	v_ashrrev_i32_e32 v8, 5, v99
	v_cmp_le_i32_e32 vcc, v1, v8
	v_ashrrev_i32_e32 v11, 6, v114
	s_nop 0
	v_cndmask_b32_e32 v2, 0, v4, vcc
	v_cmp_lt_i32_e32 vcc, v1, v8
	s_nop 1
	v_cndmask_b32_e32 v3, 0, v5, vcc
	v_cmp_le_i32_e32 vcc, v36, v8
	v_cvt_pk_bf16_f32 v2, v2, v3
	s_nop 0
	v_cndmask_b32_e32 v3, 0, v6, vcc
	v_cmp_le_i32_e32 vcc, v37, v8
	s_nop 1
	v_cndmask_b32_e32 v4, 0, v7, vcc
	v_cvt_pk_bf16_f32 v3, v3, v4
	v_mad_u64_u32 v[4:5], s[2:3], v8, s77, v[0:1]
	ds_write_b64 v4, v[2:3]
	v_ashrrev_i32_e32 v4, 5, v98
	v_cmp_le_i32_e32 vcc, v1, v4
	s_nop 1
	v_cndmask_b32_e32 v2, 0, v12, vcc
	v_cmp_lt_i32_e32 vcc, v1, v4
	s_nop 1
	v_cndmask_b32_e32 v3, 0, v13, vcc
	v_cmp_le_i32_e32 vcc, v36, v4
	v_cvt_pk_bf16_f32 v2, v2, v3
	s_nop 0
	v_cndmask_b32_e32 v3, 0, v14, vcc
	v_cmp_le_i32_e32 vcc, v37, v4
	s_nop 1
	v_cndmask_b32_e32 v5, 0, v15, vcc
	v_cvt_pk_bf16_f32 v3, v3, v5
	v_mad_u64_u32 v[4:5], s[2:3], v4, s77, v[0:1]
	ds_write_b64 v4, v[2:3]
	v_ashrrev_i32_e32 v4, 5, v97
	v_cmp_le_i32_e32 vcc, v1, v4
	s_nop 1
	v_cndmask_b32_e32 v2, 0, v16, vcc
	v_cmp_lt_i32_e32 vcc, v1, v4
	s_nop 1
	v_cndmask_b32_e32 v3, 0, v17, vcc
	v_cmp_le_i32_e32 vcc, v36, v4
	v_cvt_pk_bf16_f32 v2, v2, v3
	s_nop 0
	v_cndmask_b32_e32 v3, 0, v18, vcc
	v_cmp_le_i32_e32 vcc, v37, v4
	s_nop 1
	v_cndmask_b32_e32 v5, 0, v19, vcc
	v_cvt_pk_bf16_f32 v3, v3, v5
	v_mad_u64_u32 v[4:5], s[2:3], v4, s77, v[0:1]
	ds_write_b64 v4, v[2:3]
	v_add_u32_e32 v2, 0x800, v114
	v_ashrrev_i32_e32 v4, 5, v2
	v_cmp_le_i32_e32 vcc, v1, v4
	s_nop 1
	v_cndmask_b32_e32 v2, 0, v20, vcc
	v_cmp_lt_i32_e32 vcc, v1, v4
	s_nop 1
	v_cndmask_b32_e32 v3, 0, v21, vcc
	v_cmp_le_i32_e32 vcc, v36, v4
	v_cvt_pk_bf16_f32 v2, v2, v3
	s_nop 0
	v_cndmask_b32_e32 v3, 0, v22, vcc
	v_cmp_le_i32_e32 vcc, v37, v4
	s_nop 1
	v_cndmask_b32_e32 v5, 0, v23, vcc
	v_cvt_pk_bf16_f32 v3, v3, v5
	v_mad_u64_u32 v[4:5], s[2:3], v4, s77, v[0:1]
	ds_write_b64 v4, v[2:3]
	v_add_u32_e32 v2, 0xa00, v114
; __device__ __forceinline__ float bf2f(bf16_t b) { return __uint_as_float(((unsigned)b) << 16); }
; __device__ __forceinline__ bf16_t f2bf(float f) { unsigned u = __float_as_uint(f); u += 0x7FFFu + ((u >> 16) & 1u); return (bf16_t)(u >> 16); }
; __device__ __forceinline__ void sg_item(const Bufs& B, int l, int s, int it, unsigned char* shm) {
;     ...
;     __syncthreads();
;     const float* sb = IN(20) + (l * 4 + g) * 128;
;     for (int tile = wid; tile < 64; tile += 8) {
;         const int tm = tile >> 3, tn = tile & 7;
;         const int Kc = ((tm * 16 + 16 + 31) >> 5) << 5;
;         const f32x4 acc = mma_tile(Wm + tm * 16 * 136, 136, VnT + tn * 16 * 136, 136, Kc, lane);
;         const int c = tn * 16 + (lane & 15);
; #pragma unroll
;         for (int j = 0; j < 4; ++j) { const int tq = tm * 16 + (lane >> 4) * 4 + j;
;             B.br[2 * VEC_STRIDE + (size_t)(m0 + tq) * 512 + g * 128 + c] = f2bf(bf2f(uS[tq * 136 + c]) * (acc[j] + sb[tq])); }
;     }
	v_ashrrev_i32_e32 v4, 5, v2
	v_cmp_le_i32_e32 vcc, v1, v4
	s_nop 1
	v_cndmask_b32_e32 v2, 0, v24, vcc
	v_cmp_lt_i32_e32 vcc, v1, v4
	s_nop 1
	v_cndmask_b32_e32 v3, 0, v25, vcc
	v_cmp_le_i32_e32 vcc, v36, v4
	v_cvt_pk_bf16_f32 v2, v2, v3
	s_nop 0
	v_cndmask_b32_e32 v3, 0, v26, vcc
	v_cmp_le_i32_e32 vcc, v37, v4
	s_nop 1
	v_cndmask_b32_e32 v5, 0, v27, vcc
	v_cvt_pk_bf16_f32 v3, v3, v5
	v_mad_u64_u32 v[4:5], s[2:3], v4, s77, v[0:1]
	ds_write_b64 v4, v[2:3]
	v_add_u32_e32 v2, 0xc00, v114
	v_ashrrev_i32_e32 v4, 5, v2
	v_cmp_le_i32_e32 vcc, v1, v4
	s_nop 1
	v_cndmask_b32_e32 v2, 0, v28, vcc
	v_cmp_lt_i32_e32 vcc, v1, v4
	s_nop 1
	v_cndmask_b32_e32 v3, 0, v29, vcc
	v_cmp_le_i32_e32 vcc, v36, v4
	v_cvt_pk_bf16_f32 v2, v2, v3
	s_nop 0
	v_cndmask_b32_e32 v3, 0, v30, vcc
	v_cmp_le_i32_e32 vcc, v37, v4
	s_nop 1
	v_cndmask_b32_e32 v5, 0, v31, vcc
	v_cvt_pk_bf16_f32 v3, v3, v5
	v_mad_u64_u32 v[4:5], s[2:3], v4, s77, v[0:1]
	ds_write_b64 v4, v[2:3]
	v_add_u32_e32 v2, 0xe00, v114
	v_ashrrev_i32_e32 v4, 5, v2
	v_cmp_le_i32_e32 vcc, v1, v4
	s_nop 1
	v_cndmask_b32_e32 v2, 0, v32, vcc
	v_cmp_lt_i32_e32 vcc, v1, v4
	s_nop 1
	v_cndmask_b32_e32 v1, 0, v33, vcc
	v_cmp_le_i32_e32 vcc, v36, v4
	v_cvt_pk_bf16_f32 v2, v2, v1
	s_nop 0
	v_cndmask_b32_e32 v1, 0, v34, vcc
	v_cmp_le_i32_e32 vcc, v37, v4
	s_nop 1
	v_cndmask_b32_e32 v3, 0, v35, vcc
	v_cvt_pk_bf16_f32 v3, v1, v3
	v_mad_u64_u32 v[0:1], s[2:3], v4, s77, v[0:1]
	ds_write_b64 v0, v[2:3]
	v_add_u32_e32 v0, s39, v176
	v_mad_u64_u32 v[2:3], s[2:3], v92, s77, v[0:1]
	ds_write_b128 v2, v[48:51]
	v_mad_u64_u32 v[2:3], s[2:3], v94, s77, v[0:1]
	ds_write_b128 v2, v[52:55]
	v_mad_u64_u32 v[2:3], s[2:3], v95, s77, v[0:1]
	v_mad_u64_u32 v[0:1], s[2:3], v96, s77, v[0:1]
	ds_write_b128 v2, v[56:59]
	ds_write_b128 v0, v[60:63]
	s_waitcnt lgkmcnt(0)
	s_barrier
	s_load_dwordx2 s[2:3], s[0:1], 0xa0
	v_and_b32_e32 v108, 15, v179
	v_bfe_u32 v109, v179, 4, 2
	v_lshrrev_b32_e32 v110, 6, v179
	v_mul_u32_u24_e32 v111, 0x110, v108
	v_lshl_add_u32 v111, v109, 4, v111
	v_readfirstlane_b32 s20, v110
	s_mul_i32 s21, s20, 0x1100
	s_add_u32 s21, s21, 0x8800
	v_add_u32_e32 v112, s21, v111
	ds_read_b128 v[0:3], v112
	ds_read_b128 v[4:7], v112 offset:64
	ds_read_b128 v[8:11], v112 offset:128
	ds_read_b128 v[12:15], v112 offset:192
	s_lshl_b32 s30, s30, 9
	v_lshlrev_b32_e32 v113, 4, v109
	s_waitcnt lgkmcnt(0)
	s_add_u32 s22, s2, s30
	s_addc_u32 s23, s3, 0
	global_load_dwordx4 v[48:51], v113, s[22:23]
	global_load_dwordx4 v[52:55], v113, s[22:23] offset:64
	global_load_dwordx4 v[56:59], v113, s[22:23] offset:128
	global_load_dwordx4 v[60:63], v113, s[22:23] offset:192
	global_load_dwordx4 v[64:67], v113, s[22:23] offset:256
	global_load_dwordx4 v[68:71], v113, s[22:23] offset:320
	global_load_dwordx4 v[72:75], v113, s[22:23] offset:384
	global_load_dwordx4 v[76:79], v113, s[22:23] offset:448
	s_lshl_b32 s2, s36, 1
	s_lshl_b32 s3, s38, 10
	s_add_u32 s2, s2, s3
	s_add_u32 s2, s2, 0x2000000
	s_add_u32 s34, s40, s2
	s_addc_u32 s35, s41, 0
	v_lshl_add_u32 v114, s20, 4, v108
	v_lshlrev_b32_e32 v114, 1, v114
	v_lshl_add_u32 v115, v109, 12, v114
	v_mul_u32_u24_e32 v117, 0x440, v109
	v_add3_u32 v114, v114, v117, s39
	ds_read_b128 v[80:83], v111
	ds_read_b128 v[84:87], v111 offset:4352
	ds_read_b128 v[88:91], v111 offset:8704
	ds_read_b128 v[92:95], v111 offset:8768
	ds_read_b128 v[96:99], v111 offset:13056
	ds_read_b128 v[100:103], v111 offset:13120
	s_waitcnt lgkmcnt(0)
	v_mfma_f32_16x16x32_bf16 v[16:19], v[80:83], v[0:3], 0
	v_mfma_f32_16x16x32_bf16 v[20:23], v[84:87], v[0:3], 0
	v_mfma_f32_16x16x32_bf16 v[24:27], v[88:91], v[0:3], 0
	v_mfma_f32_16x16x32_bf16 v[24:27], v[92:95], v[4:7], v[24:27]
	v_mfma_f32_16x16x32_bf16 v[28:31], v[96:99], v[0:3], 0
	v_mfma_f32_16x16x32_bf16 v[28:31], v[100:103], v[4:7], v[28:31]
	ds_read_b128 v[80:83], v111 offset:17408
	ds_read_b128 v[84:87], v111 offset:17472
	ds_read_b128 v[88:91], v111 offset:17536
	ds_read_b128 v[92:95], v111 offset:21760
	ds_read_b128 v[96:99], v111 offset:21824
	ds_read_b128 v[100:103], v111 offset:21888
	s_waitcnt lgkmcnt(0)
	v_mfma_f32_16x16x32_bf16 v[32:35], v[80:83], v[0:3], 0
	v_mfma_f32_16x16x32_bf16 v[32:35], v[84:87], v[4:7], v[32:35]
	v_mfma_f32_16x16x32_bf16 v[32:35], v[88:91], v[8:11], v[32:35]
	v_mfma_f32_16x16x32_bf16 v[36:39], v[92:95], v[0:3], 0
	v_mfma_f32_16x16x32_bf16 v[36:39], v[96:99], v[4:7], v[36:39]
	v_mfma_f32_16x16x32_bf16 v[36:39], v[100:103], v[8:11], v[36:39]
	ds_read_b128 v[80:83], v111 offset:26112
	ds_read_b128 v[84:87], v111 offset:26176
	ds_read_b128 v[88:91], v111 offset:26240
	ds_read_b128 v[92:95], v111 offset:26304
	s_waitcnt lgkmcnt(0)
	v_mfma_f32_16x16x32_bf16 v[40:43], v[80:83], v[0:3], 0
	v_mfma_f32_16x16x32_bf16 v[40:43], v[84:87], v[4:7], v[40:43]
	v_mfma_f32_16x16x32_bf16 v[40:43], v[88:91], v[8:11], v[40:43]
	v_mfma_f32_16x16x32_bf16 v[40:43], v[92:95], v[12:15], v[40:43]
	ds_read_b128 v[80:83], v111 offset:30464
	ds_read_b128 v[84:87], v111 offset:30528
	ds_read_b128 v[88:91], v111 offset:30592
	ds_read_b128 v[92:95], v111 offset:30656
	s_waitcnt lgkmcnt(0)
	v_mfma_f32_16x16x32_bf16 v[44:47], v[80:83], v[0:3], 0
	v_mfma_f32_16x16x32_bf16 v[44:47], v[84:87], v[4:7], v[44:47]
	v_mfma_f32_16x16x32_bf16 v[44:47], v[88:91], v[8:11], v[44:47]
	v_mfma_f32_16x16x32_bf16 v[44:47], v[92:95], v[12:15], v[44:47]
	s_nop 7
	s_nop 3
	s_waitcnt vmcnt(0)
	v_mov_b32_e32 v116, v115
	ds_read_u16 v80, v114 offset:0
	ds_read_u16 v81, v114 offset:272
	ds_read_u16 v82, v114 offset:544
	ds_read_u16 v83, v114 offset:816
	s_waitcnt lgkmcnt(0)
; __device__ __forceinline__ float bf2f(bf16_t b) { return __uint_as_float(((unsigned)b) << 16); }
; __device__ __forceinline__ bf16_t f2bf(float f) { unsigned u = __float_as_uint(f); u += 0x7FFFu + ((u >> 16) & 1u); return (bf16_t)(u >> 16); }
; __device__ __forceinline__ void sg_item(const Bufs& B, int l, int s, int it, unsigned char* shm) {
;     ...
;         const int c = tn * 16 + (lane & 15);
; #pragma unroll
;         for (int j = 0; j < 4; ++j) { const int tq = tm * 16 + (lane >> 4) * 4 + j;
;             B.br[2 * VEC_STRIDE + (size_t)(m0 + tq) * 512 + g * 128 + c] = f2bf(bf2f(uS[tq * 136 + c]) * (acc[j] + sb[tq])); }
	v_lshlrev_b32_e32 v80, 16, v80
	v_add_f32_e32 v84, v16, v48
	v_mul_f32_e32 v84, v84, v80
	v_bfe_u32 v88, v84, 16, 1
	v_add3_u32 v84, v84, v88, s78
	global_store_short_d16_hi v116, v84, s[34:35]
	v_lshlrev_b32_e32 v81, 16, v81
	v_add_f32_e32 v85, v17, v49
	v_mul_f32_e32 v85, v85, v81
	v_bfe_u32 v89, v85, 16, 1
	v_add3_u32 v85, v85, v89, s78
	global_store_short_d16_hi v116, v85, s[34:35] offset:1024
	v_lshlrev_b32_e32 v82, 16, v82
	v_add_f32_e32 v86, v18, v50
	v_mul_f32_e32 v86, v86, v82
	v_bfe_u32 v90, v86, 16, 1
	v_add3_u32 v86, v86, v90, s78
	global_store_short_d16_hi v116, v86, s[34:35] offset:2048
	v_lshlrev_b32_e32 v83, 16, v83
	v_add_f32_e32 v87, v19, v51
	v_mul_f32_e32 v87, v87, v83
	v_bfe_u32 v91, v87, 16, 1
	v_add3_u32 v87, v87, v91, s78
	global_store_short_d16_hi v116, v87, s[34:35] offset:3072
	v_add_u32_e32 v116, 0x4000, v115
	ds_read_u16 v80, v114 offset:4352
	ds_read_u16 v81, v114 offset:4624
	ds_read_u16 v82, v114 offset:4896
	ds_read_u16 v83, v114 offset:5168
	s_waitcnt lgkmcnt(0)
	v_lshlrev_b32_e32 v80, 16, v80
	v_add_f32_e32 v84, v20, v52
	v_mul_f32_e32 v84, v84, v80
	v_bfe_u32 v88, v84, 16, 1
	v_add3_u32 v84, v84, v88, s78
	global_store_short_d16_hi v116, v84, s[34:35]
	v_lshlrev_b32_e32 v81, 16, v81
	v_add_f32_e32 v85, v21, v53
	v_mul_f32_e32 v85, v85, v81
	v_bfe_u32 v89, v85, 16, 1
	v_add3_u32 v85, v85, v89, s78
	global_store_short_d16_hi v116, v85, s[34:35] offset:1024
	v_lshlrev_b32_e32 v82, 16, v82
	v_add_f32_e32 v86, v22, v54
	v_mul_f32_e32 v86, v86, v82
	v_bfe_u32 v90, v86, 16, 1
	v_add3_u32 v86, v86, v90, s78
	global_store_short_d16_hi v116, v86, s[34:35] offset:2048
	v_lshlrev_b32_e32 v83, 16, v83
	v_add_f32_e32 v87, v23, v55
	v_mul_f32_e32 v87, v87, v83
	v_bfe_u32 v91, v87, 16, 1
	v_add3_u32 v87, v87, v91, s78
	global_store_short_d16_hi v116, v87, s[34:35] offset:3072
	v_add_u32_e32 v116, 0x8000, v115
	ds_read_u16 v80, v114 offset:8704
	ds_read_u16 v81, v114 offset:8976
	ds_read_u16 v82, v114 offset:9248
	ds_read_u16 v83, v114 offset:9520
	s_waitcnt lgkmcnt(0)
	v_lshlrev_b32_e32 v80, 16, v80
	v_add_f32_e32 v84, v24, v56
	v_mul_f32_e32 v84, v84, v80
	v_bfe_u32 v88, v84, 16, 1
	v_add3_u32 v84, v84, v88, s78
	global_store_short_d16_hi v116, v84, s[34:35]
	v_lshlrev_b32_e32 v81, 16, v81
	v_add_f32_e32 v85, v25, v57
	v_mul_f32_e32 v85, v85, v81
	v_bfe_u32 v89, v85, 16, 1
	v_add3_u32 v85, v85, v89, s78
	global_store_short_d16_hi v116, v85, s[34:35] offset:1024
	v_lshlrev_b32_e32 v82, 16, v82
	v_add_f32_e32 v86, v26, v58
	v_mul_f32_e32 v86, v86, v82
	v_bfe_u32 v90, v86, 16, 1
	v_add3_u32 v86, v86, v90, s78
	global_store_short_d16_hi v116, v86, s[34:35] offset:2048
	v_lshlrev_b32_e32 v83, 16, v83
	v_add_f32_e32 v87, v27, v59
	v_mul_f32_e32 v87, v87, v83
	v_bfe_u32 v91, v87, 16, 1
	v_add3_u32 v87, v87, v91, s78
	global_store_short_d16_hi v116, v87, s[34:35] offset:3072
	v_add_u32_e32 v116, 0xc000, v115
	ds_read_u16 v80, v114 offset:13056
	ds_read_u16 v81, v114 offset:13328
	ds_read_u16 v82, v114 offset:13600
	ds_read_u16 v83, v114 offset:13872
	s_waitcnt lgkmcnt(0)
	v_lshlrev_b32_e32 v80, 16, v80
	v_add_f32_e32 v84, v28, v60
	v_mul_f32_e32 v84, v84, v80
	v_bfe_u32 v88, v84, 16, 1
	v_add3_u32 v84, v84, v88, s78
	global_store_short_d16_hi v116, v84, s[34:35]
	v_lshlrev_b32_e32 v81, 16, v81
	v_add_f32_e32 v85, v29, v61
	v_mul_f32_e32 v85, v85, v81
	v_bfe_u32 v89, v85, 16, 1
	v_add3_u32 v85, v85, v89, s78
	global_store_short_d16_hi v116, v85, s[34:35] offset:1024
	v_lshlrev_b32_e32 v82, 16, v82
	v_add_f32_e32 v86, v30, v62
	v_mul_f32_e32 v86, v86, v82
	v_bfe_u32 v90, v86, 16, 1
	v_add3_u32 v86, v86, v90, s78
	global_store_short_d16_hi v116, v86, s[34:35] offset:2048
	v_lshlrev_b32_e32 v83, 16, v83
	v_add_f32_e32 v87, v31, v63
	v_mul_f32_e32 v87, v87, v83
	v_bfe_u32 v91, v87, 16, 1
	v_add3_u32 v87, v87, v91, s78
	global_store_short_d16_hi v116, v87, s[34:35] offset:3072
	v_add_u32_e32 v116, 0x10000, v115
	ds_read_u16 v80, v114 offset:17408
	ds_read_u16 v81, v114 offset:17680
	ds_read_u16 v82, v114 offset:17952
	ds_read_u16 v83, v114 offset:18224
	s_waitcnt lgkmcnt(0)
; __device__ __forceinline__ float bf2f(bf16_t b) { return __uint_as_float(((unsigned)b) << 16); }
; __device__ __forceinline__ bf16_t f2bf(float f) { unsigned u = __float_as_uint(f); u += 0x7FFFu + ((u >> 16) & 1u); return (bf16_t)(u >> 16); }
; __device__ __forceinline__ void sg_item(const Bufs& B, int l, int s, int it, unsigned char* shm) {
;     ...
;         const int c = tn * 16 + (lane & 15);
; #pragma unroll
;         for (int j = 0; j < 4; ++j) { const int tq = tm * 16 + (lane >> 4) * 4 + j;
;             B.br[2 * VEC_STRIDE + (size_t)(m0 + tq) * 512 + g * 128 + c] = f2bf(bf2f(uS[tq * 136 + c]) * (acc[j] + sb[tq])); }
	v_lshlrev_b32_e32 v80, 16, v80
	v_add_f32_e32 v84, v32, v64
	v_mul_f32_e32 v84, v84, v80
	v_bfe_u32 v88, v84, 16, 1
	v_add3_u32 v84, v84, v88, s78
	global_store_short_d16_hi v116, v84, s[34:35]
	v_lshlrev_b32_e32 v81, 16, v81
	v_add_f32_e32 v85, v33, v65
	v_mul_f32_e32 v85, v85, v81
	v_bfe_u32 v89, v85, 16, 1
	v_add3_u32 v85, v85, v89, s78
	global_store_short_d16_hi v116, v85, s[34:35] offset:1024
	v_lshlrev_b32_e32 v82, 16, v82
	v_add_f32_e32 v86, v34, v66
	v_mul_f32_e32 v86, v86, v82
	v_bfe_u32 v90, v86, 16, 1
	v_add3_u32 v86, v86, v90, s78
	global_store_short_d16_hi v116, v86, s[34:35] offset:2048
	v_lshlrev_b32_e32 v83, 16, v83
	v_add_f32_e32 v87, v35, v67
	v_mul_f32_e32 v87, v87, v83
	v_bfe_u32 v91, v87, 16, 1
	v_add3_u32 v87, v87, v91, s78
	global_store_short_d16_hi v116, v87, s[34:35] offset:3072
	v_add_u32_e32 v116, 0x14000, v115
	ds_read_u16 v80, v114 offset:21760
	ds_read_u16 v81, v114 offset:22032
	ds_read_u16 v82, v114 offset:22304
	ds_read_u16 v83, v114 offset:22576
	s_waitcnt lgkmcnt(0)
	v_lshlrev_b32_e32 v80, 16, v80
	v_add_f32_e32 v84, v36, v68
	v_mul_f32_e32 v84, v84, v80
	v_bfe_u32 v88, v84, 16, 1
	v_add3_u32 v84, v84, v88, s78
	global_store_short_d16_hi v116, v84, s[34:35]
	v_lshlrev_b32_e32 v81, 16, v81
	v_add_f32_e32 v85, v37, v69
	v_mul_f32_e32 v85, v85, v81
	v_bfe_u32 v89, v85, 16, 1
	v_add3_u32 v85, v85, v89, s78
	global_store_short_d16_hi v116, v85, s[34:35] offset:1024
	v_lshlrev_b32_e32 v82, 16, v82
	v_add_f32_e32 v86, v38, v70
	v_mul_f32_e32 v86, v86, v82
	v_bfe_u32 v90, v86, 16, 1
	v_add3_u32 v86, v86, v90, s78
	global_store_short_d16_hi v116, v86, s[34:35] offset:2048
	v_lshlrev_b32_e32 v83, 16, v83
	v_add_f32_e32 v87, v39, v71
	v_mul_f32_e32 v87, v87, v83
	v_bfe_u32 v91, v87, 16, 1
	v_add3_u32 v87, v87, v91, s78
	global_store_short_d16_hi v116, v87, s[34:35] offset:3072
	v_add_u32_e32 v116, 0x18000, v115
	ds_read_u16 v80, v114 offset:26112
	ds_read_u16 v81, v114 offset:26384
	ds_read_u16 v82, v114 offset:26656
	ds_read_u16 v83, v114 offset:26928
	s_waitcnt lgkmcnt(0)
	v_lshlrev_b32_e32 v80, 16, v80
	v_add_f32_e32 v84, v40, v72
	v_mul_f32_e32 v84, v84, v80
	v_bfe_u32 v88, v84, 16, 1
	v_add3_u32 v84, v84, v88, s78
	global_store_short_d16_hi v116, v84, s[34:35]
	v_lshlrev_b32_e32 v81, 16, v81
	v_add_f32_e32 v85, v41, v73
	v_mul_f32_e32 v85, v85, v81
	v_bfe_u32 v89, v85, 16, 1
	v_add3_u32 v85, v85, v89, s78
	global_store_short_d16_hi v116, v85, s[34:35] offset:1024
	v_lshlrev_b32_e32 v82, 16, v82
	v_add_f32_e32 v86, v42, v74
	v_mul_f32_e32 v86, v86, v82
	v_bfe_u32 v90, v86, 16, 1
	v_add3_u32 v86, v86, v90, s78
	global_store_short_d16_hi v116, v86, s[34:35] offset:2048
	v_lshlrev_b32_e32 v83, 16, v83
	v_add_f32_e32 v87, v43, v75
	v_mul_f32_e32 v87, v87, v83
	v_bfe_u32 v91, v87, 16, 1
	v_add3_u32 v87, v87, v91, s78
	global_store_short_d16_hi v116, v87, s[34:35] offset:3072
	v_add_u32_e32 v116, 0x1c000, v115
	ds_read_u16 v80, v114 offset:30464
	ds_read_u16 v81, v114 offset:30736
	ds_read_u16 v82, v114 offset:31008
	ds_read_u16 v83, v114 offset:31280
	s_waitcnt lgkmcnt(0)
	v_lshlrev_b32_e32 v80, 16, v80
	v_add_f32_e32 v84, v44, v76
	v_mul_f32_e32 v84, v84, v80
	v_bfe_u32 v88, v84, 16, 1
	v_add3_u32 v84, v84, v88, s78
	global_store_short_d16_hi v116, v84, s[34:35]
	v_lshlrev_b32_e32 v81, 16, v81
	v_add_f32_e32 v85, v45, v77
	v_mul_f32_e32 v85, v85, v81
	v_bfe_u32 v89, v85, 16, 1
	v_add3_u32 v85, v85, v89, s78
	global_store_short_d16_hi v116, v85, s[34:35] offset:1024
	v_lshlrev_b32_e32 v82, 16, v82
	v_add_f32_e32 v86, v46, v78
	v_mul_f32_e32 v86, v86, v82
	v_bfe_u32 v90, v86, 16, 1
	v_add3_u32 v86, v86, v90, s78
	global_store_short_d16_hi v116, v86, s[34:35] offset:2048
	v_lshlrev_b32_e32 v83, 16, v83
	v_add_f32_e32 v87, v47, v79
	v_mul_f32_e32 v87, v87, v83
	v_bfe_u32 v91, v87, 16, 1
	v_add3_u32 v87, v87, v91, s78
	global_store_short_d16_hi v116, v87, s[34:35] offset:3072
	s_mov_b64 s[20:21], exec
	s_branch .LBB0_546
